# MoE weight conversion split: attention hosts 12 of 16 items per wave, idle workgroups of the top-k phase convert the rest; on top of i1
# baseline (speedup 1.0000x reference)
; #define SBAR() __builtin_amdgcn_sched_barrier(0)
;   #define DMA_K(t,slot) glds16(ksrc+(long)(t)*KVBLK*kp,(unsigned)__builtin_amdgcn_readfirstlane(kdst+(slot)))
;   #define DMA_V(t,slot) glds16(vsrc+(long)(t)*KVBLK*vp,(unsigned)__builtin_amdgcn_readfirstlane(vdst+(slot)))
;   #define DMA_K(t,slot) glds16(ksrc+(long)(t)*KVBLK*kp,(unsigned)__builtin_amdgcn_readfirstlane(kdst+(slot)))
;   #define DMA_V(t,slot) glds16(vsrc+(long)(t)*KVBLK*vp,(unsigned)__builtin_amdgcn_readfirstlane(vdst+(slot)))
; __device__ __forceinline__ void attn_unit2(const bf16*Qu,int qp,const bf16*__restrict__ Kh,int kp,const bf16*__restrict__ Vh,int vp,bf16*Ou,int op,int NT,char*shm,int tid_in){
;     ...
;     if(t>0){ if(t+2<NT) asm volatile("s_waitcnt vmcnt(2) lgkmcnt(0)\n\ts_barrier":::"memory"); else asm volatile("s_waitcnt vmcnt(0) lgkmcnt(0)\n\ts_barrier":::"memory"); }
;     if(t+3<NT){DMA_K(t+3,sl_n3);DMA_V(t+3,sl_n3);}
;     const bool nx=t+1<NT; const lds_cptr vq=vp0+sl_cur; s16x4 vlo[8],vhi[8]; float sa=0.f,sb=0.f;
;     ...
;     b0=MF(kf[0],qb[0],z16); SP4(sa,a0,0,pa[0],0);  b1=MF(kf[1],qb[0],z16); SP4(sa,a0,4,pa[0],1);
;     b0=MF(kf[2],qb[1],b0);  SP4(sa,a0,8,pa[1],0);  b1=MF(kf[3],qb[1],b1);  SP4(sa,a0,12,pa[1],1);
;     b0=MF(kf[4],qb[2],b0);  SP4(sa,a1,0,pa[2],0);  b1=MF(kf[5],qb[2],b1);  SP4(sa,a1,4,pa[2],1);
;     b0=MF(kf[6],qb[3],b0);  SP4(sa,a1,8,pa[3],0);  b1=MF(kf[7],qb[3],b1);  SP4(sa,a1,12,pa[3],1);
;     la+=sa;
;     VLD(); if(nx) kload8(kf,kp0+sl_n1);
;     ...
;     PVA(0,0); X4(b0,0); PVA(0,1); X4(b0,4); PVA(1,0); X4(b0,8); PVA(1,1); X4(b0,12);
;     PVA(2,0); X4(b1,0); PVA(2,1); X4(b1,4); PVA(3,0); X4(b1,8); PVA(3,1); X4(b1,12);
;     if(nx){ a0=MF(kf[0],qa[0],z16); } SP4(sb,b0,0,pb[0],0);  if(nx){ a1=MF(kf[1],qa[0],z16); } SP4(sb,b0,4,pb[0],1);
;     if(nx){ a0=MF(kf[2],qa[1],a0); }  SP4(sb,b0,8,pb[1],0);  if(nx){ a1=MF(kf[3],qa[1],a1); }  SP4(sb,b0,12,pb[1],1);
;     if(nx){ a0=MF(kf[4],qa[2],a0); }  SP4(sb,b1,0,pb[2],0);  if(nx){ a1=MF(kf[5],qa[2],a1); }  SP4(sb,b1,4,pb[2],1);
;     if(nx){ a0=MF(kf[6],qa[3],a0); }  SP4(sb,b1,8,pb[3],0);  if(nx){ a1=MF(kf[7],qa[3],a1); }  SP4(sb,b1,12,pb[3],1);
;     lb+=sb;
;     VLD(); SBAR();
;     PVB(0,0); if(nx) X4(a0,0); PVB(0,1); if(nx) X4(a0,4); PVB(1,0); if(nx) X4(a0,8); PVB(1,1); if(nx) X4(a0,12);
;     PVB(2,0); if(nx) X4(a1,0); PVB(2,1); if(nx) X4(a1,4); PVB(3,0); if(nx) X4(a1,8); PVB(3,1); if(nx) X4(a1,12);
.LBB0_903:
	v_add_u32_e32 v170, s14, v0
	v_add_f32_e32 v0, 0, v82
	s_waitcnt vmcnt(0) lgkmcnt(0)
	s_barrier
	v_add_f32_e32 v0, v83, v0
	v_add_f32_e32 v0, v84, v0
	v_add_f32_e32 v0, v85, v0
	v_cvt_pk_bf16_f32 v158, v82, v83
	v_cvt_pk_bf16_f32 v159, v84, v85
	s_nop 0
	v_add_f32_e32 v0, v86, v0
	v_add_f32_e32 v0, v87, v0
	v_add_f32_e32 v0, v88, v0
	v_add_f32_e32 v0, v89, v0
	v_cvt_pk_bf16_f32 v160, v86, v87
	v_cvt_pk_bf16_f32 v161, v88, v89
	s_nop 0
	v_add_f32_e32 v0, v90, v0
	v_add_f32_e32 v0, v91, v0
	v_add_f32_e32 v0, v92, v0
	v_add_f32_e32 v0, v93, v0
	v_cvt_pk_bf16_f32 v154, v90, v91
	v_cvt_pk_bf16_f32 v155, v92, v93
	s_nop 0
	v_add_f32_e32 v0, v94, v0
	v_add_f32_e32 v0, v95, v0
	v_add_f32_e32 v0, v96, v0
	v_add_f32_e32 v0, v97, v0
	v_cvt_pk_bf16_f32 v156, v94, v95
	v_cvt_pk_bf16_f32 v157, v96, v97
	s_nop 0
	v_add_f32_e32 v0, v66, v0
	v_add_f32_e32 v0, v67, v0
	v_add_f32_e32 v0, v68, v0
	v_add_f32_e32 v0, v69, v0
	v_cvt_pk_bf16_f32 v138, v66, v67
	v_cvt_pk_bf16_f32 v139, v68, v69
	s_nop 0
	v_add_f32_e32 v0, v70, v0
	v_add_f32_e32 v0, v71, v0
	v_add_f32_e32 v0, v72, v0
	v_add_f32_e32 v0, v73, v0
	v_cvt_pk_bf16_f32 v140, v70, v71
	v_cvt_pk_bf16_f32 v141, v72, v73
	s_nop 0
	v_add_f32_e32 v0, v74, v0
	v_add_f32_e32 v0, v75, v0
	v_add_f32_e32 v0, v76, v0
	v_add_f32_e32 v0, v77, v0
	v_cvt_pk_bf16_f32 v134, v74, v75
	v_cvt_pk_bf16_f32 v135, v76, v77
	s_nop 0
	v_add_f32_e32 v0, v78, v0
	v_add_f32_e32 v0, v79, v0
	v_add_f32_e32 v0, v80, v0
	v_add_f32_e32 v0, v81, v0
	v_cvt_pk_bf16_f32 v136, v78, v79
	v_cvt_pk_bf16_f32 v137, v80, v81
	v_mfma_f32_32x32x16_bf16 v[82:97], v[206:209], v[150:153], 0
	ds_read_b64_tr_b16 v[98:99], v170 offset:32768
	ds_read_b64_tr_b16 v[100:101], v170 offset:33280
	ds_read_b64_tr_b16 v[102:103], v170 offset:33792
	ds_read_b64_tr_b16 v[104:105], v170 offset:34304
	ds_read_b64_tr_b16 v[106:107], v170 offset:34816
	ds_read_b64_tr_b16 v[108:109], v170 offset:35328
	ds_read_b64_tr_b16 v[110:111], v170 offset:35840
	ds_read_b64_tr_b16 v[112:113], v170 offset:36352
	ds_read_b64_tr_b16 v[114:115], v170 offset:36864
	ds_read_b64_tr_b16 v[116:117], v170 offset:37376
	ds_read_b64_tr_b16 v[118:119], v170 offset:37888
	ds_read_b64_tr_b16 v[120:121], v170 offset:38400
	ds_read_b64_tr_b16 v[122:123], v170 offset:38912
	ds_read_b64_tr_b16 v[124:125], v170 offset:39424
	ds_read_b64_tr_b16 v[126:127], v170 offset:39936
	ds_read_b64_tr_b16 v[128:129], v170 offset:40448
	v_add_f32_e32 v0, v226, v0
	v_mfma_f32_32x32x16_bf16 v[66:81], v[210:213], v[150:153], 0
	v_mfma_f32_32x32x16_bf16 v[82:97], v[202:205], v[146:149], v[82:97]
	v_mfma_f32_32x32x16_bf16 v[66:81], v[198:201], v[146:149], v[66:81]
	v_mfma_f32_32x32x16_bf16 v[82:97], v[222:225], v[142:145], v[82:97]
	v_mfma_f32_32x32x16_bf16 v[66:81], v[218:221], v[142:145], v[66:81]
	v_mfma_f32_32x32x16_bf16 v[82:97], v[214:217], v[130:133], v[82:97]
	v_mfma_f32_32x32x16_bf16 v[66:81], v[194:197], v[130:133], v[66:81]
	s_nop 10
	v_exp_f32_e32 v82, v82
	v_exp_f32_e32 v83, v83
	v_exp_f32_e32 v84, v84
	v_exp_f32_e32 v85, v85
	s_waitcnt lgkmcnt(14)
	v_mfma_f32_32x32x16_bf16 v[2:17], v[158:161], v[98:101], v[2:17]
	s_waitcnt lgkmcnt(6)
	v_mfma_f32_32x32x16_bf16 v[18:33], v[158:161], v[114:117], v[18:33]
	v_exp_f32_e32 v86, v86
	v_exp_f32_e32 v87, v87
	v_exp_f32_e32 v88, v88
	v_exp_f32_e32 v89, v89
	v_mfma_f32_32x32x16_bf16 v[2:17], v[154:157], v[102:105], v[2:17]
	v_exp_f32_e32 v90, v90
	v_exp_f32_e32 v91, v91
	v_exp_f32_e32 v92, v92
	v_exp_f32_e32 v93, v93
	s_waitcnt lgkmcnt(4)
	v_mfma_f32_32x32x16_bf16 v[18:33], v[154:157], v[118:121], v[18:33]
	v_exp_f32_e32 v94, v94
	v_exp_f32_e32 v95, v95
	v_exp_f32_e32 v96, v96
	v_exp_f32_e32 v97, v97
	v_mfma_f32_32x32x16_bf16 v[2:17], v[138:141], v[106:109], v[2:17]
	v_exp_f32_e32 v66, v66
	v_exp_f32_e32 v67, v67
	v_exp_f32_e32 v68, v68
	v_exp_f32_e32 v69, v69
	s_waitcnt lgkmcnt(2)
	v_mfma_f32_32x32x16_bf16 v[18:33], v[138:141], v[122:125], v[18:33]
	v_exp_f32_e32 v70, v70
	v_exp_f32_e32 v71, v71
	v_exp_f32_e32 v72, v72
	v_exp_f32_e32 v73, v73
	v_mfma_f32_32x32x16_bf16 v[2:17], v[134:137], v[110:113], v[2:17]
	v_exp_f32_e32 v74, v74
	v_exp_f32_e32 v75, v75
	v_exp_f32_e32 v76, v76
	v_exp_f32_e32 v77, v77
	s_waitcnt lgkmcnt(0)
	v_mfma_f32_32x32x16_bf16 v[18:33], v[134:137], v[126:129], v[18:33]
	v_exp_f32_e32 v78, v78
	v_exp_f32_e32 v79, v79
	v_exp_f32_e32 v80, v80
	v_exp_f32_e32 v81, v81
	v_add_f32_e32 v98, 0, v82
	v_add_f32_e32 v98, v83, v98
	v_add_f32_e32 v98, v84, v98
	v_add_f32_e32 v98, v85, v98
	v_cvt_pk_bf16_f32 v162, v82, v83
	v_cvt_pk_bf16_f32 v163, v84, v85
	s_nop 0
	v_add_f32_e32 v82, v86, v98
	v_add_f32_e32 v82, v87, v82
	v_add_f32_e32 v82, v88, v82
	v_add_f32_e32 v82, v89, v82
	v_cvt_pk_bf16_f32 v164, v86, v87
	v_cvt_pk_bf16_f32 v165, v88, v89
	s_nop 0
	v_add_f32_e32 v82, v90, v82
	v_add_f32_e32 v82, v91, v82
	v_add_f32_e32 v82, v92, v82
	v_add_f32_e32 v82, v93, v82
	v_cvt_pk_bf16_f32 v166, v90, v91
	v_cvt_pk_bf16_f32 v167, v92, v93
	s_nop 0
	v_add_f32_e32 v82, v94, v82
	v_add_f32_e32 v82, v95, v82
	v_add_f32_e32 v82, v96, v82
	v_add_f32_e32 v82, v97, v82
	v_cvt_pk_bf16_f32 v168, v94, v95
	v_cvt_pk_bf16_f32 v169, v96, v97
	s_nop 0
	v_add_f32_e32 v82, v66, v82
	v_add_f32_e32 v82, v67, v82
	v_add_f32_e32 v82, v68, v82
	v_add_f32_e32 v82, v69, v82
	v_cvt_pk_bf16_f32 v186, v66, v67
	v_cvt_pk_bf16_f32 v187, v68, v69
	s_nop 0
	v_add_f32_e32 v66, v70, v82
	v_add_f32_e32 v66, v71, v66
	v_add_f32_e32 v66, v72, v66
	v_add_f32_e32 v66, v73, v66
	v_cvt_pk_bf16_f32 v188, v70, v71
	v_cvt_pk_bf16_f32 v189, v72, v73
	s_nop 0
	v_add_f32_e32 v66, v74, v66
	v_add_f32_e32 v66, v75, v66
	v_add_f32_e32 v66, v76, v66
	v_add_f32_e32 v66, v77, v66
	v_cvt_pk_bf16_f32 v190, v74, v75
	v_cvt_pk_bf16_f32 v191, v76, v77
	s_nop 0
	v_add_f32_e32 v66, v78, v66
	v_add_f32_e32 v66, v79, v66
	v_add_f32_e32 v66, v80, v66
	v_add_f32_e32 v66, v81, v66
	v_cvt_pk_bf16_f32 v192, v78, v79
	v_cvt_pk_bf16_f32 v193, v80, v81
	ds_read_b64_tr_b16 v[68:69], v170 offset:32768
	ds_read_b64_tr_b16 v[70:71], v170 offset:33280
	ds_read_b64_tr_b16 v[72:73], v170 offset:33792
	ds_read_b64_tr_b16 v[74:75], v170 offset:34304
	ds_read_b64_tr_b16 v[76:77], v170 offset:34816
	ds_read_b64_tr_b16 v[78:79], v170 offset:35328
	ds_read_b64_tr_b16 v[80:81], v170 offset:35840
	ds_read_b64_tr_b16 v[82:83], v170 offset:36352
	ds_read_b64_tr_b16 v[84:85], v170 offset:36864
	ds_read_b64_tr_b16 v[86:87], v170 offset:37376
	ds_read_b64_tr_b16 v[88:89], v170 offset:37888
	ds_read_b64_tr_b16 v[90:91], v170 offset:38400
	ds_read_b64_tr_b16 v[92:93], v170 offset:38912
	ds_read_b64_tr_b16 v[94:95], v170 offset:39424
	ds_read_b64_tr_b16 v[96:97], v170 offset:39936
	ds_read_b64_tr_b16 v[98:99], v170 offset:40448
	s_waitcnt lgkmcnt(14)
; __device__ __forceinline__ int crow(int r,int hi){return (r&3)+8*(r>>2)+4*hi;}
; #define SBAR() __builtin_amdgcn_sched_barrier(0)
;   #define X4(P,B) do{ P[B]=__builtin_amdgcn_exp2f(P[B]); P[B+1]=__builtin_amdgcn_exp2f(P[B+1]); P[B+2]=__builtin_amdgcn_exp2f(P[B+2]); P[B+3]=__builtin_amdgcn_exp2f(P[B+3]); asm volatile("":"+v"(P)); SBAR(); }while(0)
;     #define PVB(ks,d0) ob[d0]=MF(__builtin_bit_cast(bf16x8,pb[ks]),VF((ks)+4*(d0)),ob[d0])
; __device__ __forceinline__ void attn_unit2(const bf16*Qu,int qp,const bf16*__restrict__ Kh,int kp,const bf16*__restrict__ Vh,int vp,bf16*Ou,int op,int NT,char*shm,int tid_in){
;     ...
;     PVB(0,0); if(nx) X4(a0,0); PVB(0,1); if(nx) X4(a0,4); PVB(1,0); if(nx) X4(a0,8); PVB(1,1); if(nx) X4(a0,12);
;     PVB(2,0); if(nx) X4(a1,0); PVB(2,1); if(nx) X4(a1,4); PVB(3,0); if(nx) X4(a1,8); PVB(3,1); if(nx) X4(a1,12);
;     SBAR();
;     ...
;     sl_cur=(sl_cur==3*SLOTB)?0:sl_cur+SLOTB; sl_n1=(sl_n1==3*SLOTB)?0:sl_n1+SLOTB; sl_n3=(sl_n3==3*SLOTB)?0:sl_n3+SLOTB;
;   }
;     ...
;   bf16*stg=(bf16*)(shm+U2_OST)+wid*2048;
;   #pragma unroll
;   for(int blk=0;blk<2;++blk){ float l_reg=blk?lb:la; const f32x16 o0=blk?ob[0]:oa[0], o1=blk?ob[1]:oa[1];
;     {auto rr=__builtin_amdgcn_permlane32_swap(__float_as_uint(l_reg),__float_as_uint(l_reg),false,false);l_reg=__uint_as_float(rr[0])+__uint_as_float(rr[1]);}
;     if(hi==0)wsf[32+r32]=l_reg;asm volatile("s_waitcnt lgkmcnt(0)":::"memory");
;     float rli[16];
;     #pragma unroll
;     for(int r=0;r<16;++r)rli[r]=__builtin_amdgcn_rcpf(wsf[32+crow(r,hi)]);
;     #pragma unroll
;     for(int r=0;r<16;++r){const int orow=crow(r,hi); stg[orow*64+r32]=__float2bfloat16(o0[r]*rli[r]); stg[orow*64+32+r32]=__float2bfloat16(o1[r]*rli[r]);}
;     asm volatile("s_waitcnt lgkmcnt(0)":::"memory");
;     bf16*Ow=Ou+(long)(wid*64+blk*32)*op;
;     #pragma unroll
;     for(int i=0;i<4;++i){const int row=i*8+(lane>>3),ch=lane&7; const u32x4 v=*(const u32x4*)(stg+row*64+ch*8); ATTN_STORE16(Ow+(long)row*op+ch*8,v);}
;     asm volatile("s_waitcnt lgkmcnt(0)":::"memory"); }
	v_mfma_f32_32x32x16_bf16 v[34:49], v[162:165], v[68:71], v[34:49]
	s_waitcnt lgkmcnt(6)
	v_mfma_f32_32x32x16_bf16 v[50:65], v[162:165], v[84:87], v[50:65]
	v_mfma_f32_32x32x16_bf16 v[34:49], v[166:169], v[72:75], v[34:49]
	s_waitcnt lgkmcnt(4)
	v_mfma_f32_32x32x16_bf16 v[50:65], v[166:169], v[88:91], v[50:65]
	v_mfma_f32_32x32x16_bf16 v[34:49], v[186:189], v[76:79], v[34:49]
	s_waitcnt lgkmcnt(2)
	v_mfma_f32_32x32x16_bf16 v[50:65], v[186:189], v[92:95], v[50:65]
	v_mfma_f32_32x32x16_bf16 v[34:49], v[190:193], v[80:83], v[34:49]
	s_waitcnt lgkmcnt(0)
	v_mfma_f32_32x32x16_bf16 v[50:65], v[190:193], v[96:99], v[50:65]
	s_lshl_b32 s3, s2, 2
	s_add_i32 s3, s3, 0
	s_add_i32 s3, s3, 0x10000
	v_mov_b32_e32 v67, v0
	v_cmp_gt_u32_e32 vcc, 32, v249
	v_lshl_add_u32 v68, v251, 2, s3
	v_permlane32_swap_b32_e32 v0, v67
	s_and_saveexec_b64 s[8:9], vcc
	v_add_f32_e32 v0, v0, v67
	ds_write_b32 v68, v0 offset:128
	s_or_b64 exec, exec, s[8:9]
	v_add_f32_e32 v70, v227, v66
	v_lshlrev_b32_e32 v66, 4, v238
	s_waitcnt lgkmcnt(0)
	v_add_u32_e32 v69, s3, v66
	ds_read_b128 v[72:75], v69 offset:128
	ds_read_b128 v[76:79], v69 offset:160
	s_add_u32 s6, s50, s6
	s_addc_u32 s7, s51, s7
	s_lshl_b32 s8, s10, 1
	s_add_u32 s6, s6, s8
	s_waitcnt lgkmcnt(1)
	v_rcp_f32_e32 v83, v72
	v_rcp_f32_e32 v84, v73
	s_addc_u32 s7, s7, 0
	s_lshl_b32 s8, s11, 12
	s_add_i32 s8, s8, 0
	s_add_i32 s8, s8, 0x10800
	v_lshl_add_u32 v80, v251, 1, s8
	v_lshlrev_b32_e32 v81, 9, v238
	v_rcp_f32_e32 v85, v74
	v_mul_f32_e32 v2, v2, v83
	v_mul_f32_e32 v3, v3, v84
	v_cvt_pk_bf16_f32 v91, v2, s0
	v_add_u32_e32 v2, v80, v81
	v_cvt_pk_bf16_f32 v3, v3, s0
	v_rcp_f32_e32 v86, v75
	s_waitcnt lgkmcnt(0)
	v_rcp_f32_e32 v87, v76
	ds_read_b128 v[72:75], v69 offset:192
	v_rcp_f32_e32 v88, v77
	v_rcp_f32_e32 v89, v78
	v_rcp_f32_e32 v90, v79
	ds_read_b128 v[76:79], v69 offset:224
	ds_write_b16 v2, v3 offset:128
	v_mul_f32_e32 v3, v19, v84
	v_cvt_pk_bf16_f32 v3, v3, s0
	ds_write_b16 v2, v3 offset:192
	v_mul_f32_e32 v3, v4, v85
	v_cvt_pk_bf16_f32 v3, v3, s0
	ds_write_b16 v2, v3 offset:256
	v_mul_f32_e32 v3, v20, v85
	v_cvt_pk_bf16_f32 v3, v3, s0
	ds_write_b16 v2, v3 offset:320
	v_mul_f32_e32 v3, v5, v86
	v_cvt_pk_bf16_f32 v3, v3, s0
	ds_write_b16 v2, v3 offset:384
	v_mul_f32_e32 v3, v21, v86
	v_cvt_pk_bf16_f32 v3, v3, s0
	ds_write_b16 v2, v3 offset:448
	v_mul_f32_e32 v3, v6, v87
	v_cvt_pk_bf16_f32 v3, v3, s0
	ds_write_b16 v2, v3 offset:1024
	v_mul_f32_e32 v3, v22, v87
	v_cvt_pk_bf16_f32 v3, v3, s0
	ds_write_b16 v2, v3 offset:1088
	v_mul_f32_e32 v3, v7, v88
	v_cvt_pk_bf16_f32 v3, v3, s0
	ds_write_b16 v2, v3 offset:1152
	v_mul_f32_e32 v3, v23, v88
	v_cvt_pk_bf16_f32 v3, v3, s0
	ds_write_b16 v2, v3 offset:1216
	v_mul_f32_e32 v3, v8, v89
	v_cvt_pk_bf16_f32 v3, v3, s0
	ds_write_b16 v2, v3 offset:1280
	v_mul_f32_e32 v3, v24, v89
	v_cvt_pk_bf16_f32 v3, v3, s0
	s_waitcnt lgkmcnt(12)
	v_rcp_f32_e32 v72, v72
	ds_write_b16 v2, v3 offset:1344
	v_mul_f32_e32 v3, v9, v90
	v_cvt_pk_bf16_f32 v3, v3, s0
	ds_write_b16 v2, v3 offset:1408
	v_mul_f32_e32 v3, v25, v90
	v_cvt_pk_bf16_f32 v3, v3, s0
	v_rcp_f32_e32 v73, v73
	ds_write_b16 v2, v3 offset:1472
	v_mul_f32_e32 v3, v10, v72
	v_cvt_pk_bf16_f32 v3, v3, s0
	ds_write_b16 v2, v3 offset:2048
	v_mul_f32_e32 v3, v26, v72
	v_cvt_pk_bf16_f32 v3, v3, s0
	v_rcp_f32_e32 v74, v74
	ds_write_b16 v2, v3 offset:2112
	v_mul_f32_e32 v3, v11, v73
	v_cvt_pk_bf16_f32 v3, v3, s0
	ds_write_b16 v2, v3 offset:2176
	v_mul_f32_e32 v3, v27, v73
	v_cvt_pk_bf16_f32 v3, v3, s0
	v_rcp_f32_e32 v75, v75
	ds_write_b16 v2, v3 offset:2240
	v_mul_f32_e32 v3, v12, v74
	v_cvt_pk_bf16_f32 v3, v3, s0
	ds_write_b16 v2, v3 offset:2304
	v_mul_f32_e32 v3, v28, v74
	v_cvt_pk_bf16_f32 v3, v3, s0
	s_waitcnt lgkmcnt(14)
	v_rcp_f32_e32 v76, v76
	ds_write_b16 v2, v3 offset:2368
	v_mul_f32_e32 v3, v13, v75
	v_cvt_pk_bf16_f32 v3, v3, s0
	ds_write_b16 v2, v3 offset:2432
	v_mul_f32_e32 v3, v29, v75
	v_cvt_pk_bf16_f32 v3, v3, s0
	v_rcp_f32_e32 v77, v77
	ds_write_b16 v2, v3 offset:2496
	v_mul_f32_e32 v3, v14, v76
	v_cvt_pk_bf16_f32 v3, v3, s0
	ds_write_b16 v2, v3 offset:3072
	v_mul_f32_e32 v3, v30, v76
	v_cvt_pk_bf16_f32 v3, v3, s0
	v_rcp_f32_e32 v78, v78
	ds_write_b16 v2, v3 offset:3136
	v_mul_f32_e32 v3, v15, v77
	v_cvt_pk_bf16_f32 v3, v3, s0
	ds_write_b16 v2, v3 offset:3200
	v_mul_f32_e32 v3, v31, v77
	v_cvt_pk_bf16_f32 v3, v3, s0
	v_rcp_f32_e32 v79, v79
	ds_write_b16 v2, v3 offset:3264
	v_mul_f32_e32 v3, v16, v78
	v_cvt_pk_bf16_f32 v3, v3, s0
	ds_write_b16 v2, v3 offset:3328
	v_mul_f32_e32 v3, v32, v78
	v_cvt_pk_bf16_f32 v3, v3, s0
	ds_write_b16 v2, v3 offset:3392
	v_mul_f32_e32 v3, v17, v79
	v_cvt_pk_bf16_f32 v3, v3, s0
	v_lshlrev_b32_e32 v0, 1, v248
	v_mul_f32_e32 v18, v18, v83
	ds_write_b16 v2, v3 offset:3456
	v_mul_f32_e32 v3, v33, v79
	v_lshrrev_b32_e32 v71, 3, v249
	v_and_b32_e32 v0, 0x70, v0
	v_cvt_pk_bf16_f32 v18, v18, s0
	v_cvt_pk_bf16_f32 v3, v3, s0
	v_add_u32_e32 v82, s8, v0
	v_lshl_add_u64 v[66:67], s[6:7], 0, v[0:1]
	v_lshlrev_b32_e32 v0, 7, v71
	ds_write_b16 v2, v91
	ds_write_b16 v2, v18 offset:64
	ds_write_b16 v2, v3 offset:3520
	v_or_b32_e32 v7, 8, v71
	s_waitcnt lgkmcnt(0)
	v_add_u32_e32 v3, v82, v0
	v_lshlrev_b32_e32 v4, 7, v7
	ds_read_b128 v[8:11], v3
	v_add_u32_e32 v4, v82, v4
	ds_read_b128 v[12:15], v4
	v_lshl_add_u64 v[18:19], v[66:67], 0, s[4:5]
	v_lshlrev_b32_e32 v0, 10, v71
	v_lshl_add_u64 v[16:17], v[18:19], 0, v[0:1]
	v_lshlrev_b32_e32 v0, 10, v7
	s_waitcnt lgkmcnt(1)
	global_store_dwordx4 v[16:17], v[8:11], off
	s_nop 1
	v_lshl_add_u64 v[8:9], v[18:19], 0, v[0:1]
	s_waitcnt lgkmcnt(0)
; __device__ __forceinline__ int crow(int r,int hi){return (r&3)+8*(r>>2)+4*hi;}
; __device__ __forceinline__ void attn_unit2(const bf16*Qu,int qp,const bf16*__restrict__ Kh,int kp,const bf16*__restrict__ Vh,int vp,bf16*Ou,int op,int NT,char*shm,int tid_in){
;     ...
;   for(int blk=0;blk<2;++blk){ float l_reg=blk?lb:la; const f32x16 o0=blk?ob[0]:oa[0], o1=blk?ob[1]:oa[1];
;     {auto rr=__builtin_amdgcn_permlane32_swap(__float_as_uint(l_reg),__float_as_uint(l_reg),false,false);l_reg=__uint_as_float(rr[0])+__uint_as_float(rr[1]);}
;     if(hi==0)wsf[32+r32]=l_reg;asm volatile("s_waitcnt lgkmcnt(0)":::"memory");
;     float rli[16];
;     #pragma unroll
;     for(int r=0;r<16;++r)rli[r]=__builtin_amdgcn_rcpf(wsf[32+crow(r,hi)]);
;     #pragma unroll
;     for(int r=0;r<16;++r){const int orow=crow(r,hi); stg[orow*64+r32]=__float2bfloat16(o0[r]*rli[r]); stg[orow*64+32+r32]=__float2bfloat16(o1[r]*rli[r]);}
;     asm volatile("s_waitcnt lgkmcnt(0)":::"memory");
;     bf16*Ow=Ou+(long)(wid*64+blk*32)*op;
;     #pragma unroll
;     for(int i=0;i<4;++i){const int row=i*8+(lane>>3),ch=lane&7; const u32x4 v=*(const u32x4*)(stg+row*64+ch*8); ATTN_STORE16(Ow+(long)row*op+ch*8,v);}
;     asm volatile("s_waitcnt lgkmcnt(0)":::"memory"); }
;   asm volatile("s_waitcnt lgkmcnt(0)\n\ts_barrier":::"memory");
	global_store_dwordx4 v[8:9], v[12:15], off
	v_or_b32_e32 v8, 16, v71
	v_lshlrev_b32_e32 v0, 7, v8
	v_or_b32_e32 v9, 24, v71
	v_add_u32_e32 v5, v82, v0
	v_lshlrev_b32_e32 v6, 7, v9
	ds_read_b128 v[10:13], v5
	v_add_u32_e32 v6, v82, v6
	ds_read_b128 v[14:17], v6
	v_lshlrev_b32_e32 v0, 10, v8
	v_lshl_add_u64 v[20:21], v[18:19], 0, v[0:1]
	v_lshlrev_b32_e32 v0, 10, v9
	s_waitcnt lgkmcnt(1)
	global_store_dwordx4 v[20:21], v[10:13], off
	s_nop 1
	v_lshl_add_u64 v[10:11], v[18:19], 0, v[0:1]
	s_waitcnt lgkmcnt(0)
	global_store_dwordx4 v[10:11], v[14:17], off
	s_waitcnt lgkmcnt(0)
	v_mov_b32_e32 v0, v70
	s_nop 1
	v_permlane32_swap_b32_e32 v70, v0
	s_mov_b64 s[4:5], exec
	s_and_b64 s[6:7], s[4:5], vcc
	v_mov_b32_e32 v238, v239
	v_mov_b32_e32 v241, 0x358637bd
	v_mov_b32_e32 v239, 0x3727c5ac
	v_mov_b32_e32 v240, 0x7f800000
	s_mov_b64 exec, s[6:7]
	v_add_f32_e32 v0, v70, v0
	ds_write_b32 v68, v0 offset:128
	s_or_b64 exec, exec, s[4:5]
	s_waitcnt lgkmcnt(0)
	ds_read_b128 v[10:13], v69 offset:128
	ds_read_b128 v[14:17], v69 offset:160
	v_lshlrev_b32_e32 v18, 9, v8
	v_lshlrev_b32_e32 v19, 9, v9
	s_or_b32 s2, s2, 32
	s_waitcnt lgkmcnt(1)
	v_rcp_f32_e32 v20, v10
	v_rcp_f32_e32 v21, v11
	v_rcp_f32_e32 v22, v12
	v_rcp_f32_e32 v23, v13
	v_mul_f32_e32 v26, v34, v20
	v_mul_f32_e32 v20, v50, v20
	v_cvt_pk_bf16_f32 v20, v20, s0
	s_waitcnt lgkmcnt(0)
	v_rcp_f32_e32 v24, v14
	ds_read_b128 v[8:11], v69 offset:192
	v_rcp_f32_e32 v25, v15
	ds_read_b128 v[12:15], v69 offset:224
	ds_write_b16 v2, v20 offset:64
	v_mul_f32_e32 v20, v35, v21
	v_cvt_pk_bf16_f32 v20, v20, s0
	ds_write_b16 v2, v20 offset:128
	v_mul_f32_e32 v20, v51, v21
	v_cvt_pk_bf16_f32 v20, v20, s0
	ds_write_b16 v2, v20 offset:192
	v_mul_f32_e32 v20, v36, v22
	v_cvt_pk_bf16_f32 v20, v20, s0
	ds_write_b16 v2, v20 offset:256
	v_mul_f32_e32 v20, v52, v22
	v_cvt_pk_bf16_f32 v20, v20, s0
	ds_write_b16 v2, v20 offset:320
	v_mul_f32_e32 v20, v37, v23
	v_cvt_pk_bf16_f32 v20, v20, s0
	ds_write_b16 v2, v20 offset:384
	v_mul_f32_e32 v20, v53, v23
	v_cvt_pk_bf16_f32 v20, v20, s0
	ds_write_b16 v2, v20 offset:448
	v_mul_f32_e32 v20, v38, v24
	v_cvt_pk_bf16_f32 v20, v20, s0
	ds_write_b16 v2, v20 offset:1024
	v_mul_f32_e32 v20, v54, v24
	v_cvt_pk_bf16_f32 v20, v20, s0
	v_rcp_f32_e32 v16, v16
	ds_write_b16 v2, v20 offset:1088
	v_mul_f32_e32 v20, v39, v25
	v_cvt_pk_bf16_f32 v20, v20, s0
	v_rcp_f32_e32 v17, v17
	ds_write_b16 v2, v20 offset:1152
	v_mul_f32_e32 v20, v55, v25
	v_cvt_pk_bf16_f32 v20, v20, s0
	ds_write_b16 v2, v20 offset:1216
	v_mul_f32_e32 v20, v40, v16
	v_mul_f32_e32 v16, v56, v16
	v_cvt_pk_bf16_f32 v16, v16, s0
	s_waitcnt lgkmcnt(12)
	v_rcp_f32_e32 v8, v8
	ds_write_b16 v2, v16 offset:1344
	v_mul_f32_e32 v16, v41, v17
	v_cvt_pk_bf16_f32 v16, v16, s0
	v_rcp_f32_e32 v9, v9
	ds_write_b16 v2, v16 offset:1408
	v_mul_f32_e32 v16, v57, v17
	v_cvt_pk_bf16_f32 v16, v16, s0
	ds_write_b16 v2, v16 offset:1472
	v_mul_f32_e32 v16, v42, v8
	v_mul_f32_e32 v8, v58, v8
	v_cvt_pk_bf16_f32 v8, v8, s0
	v_rcp_f32_e32 v10, v10
	ds_write_b16 v2, v8 offset:2112
	v_mul_f32_e32 v8, v43, v9
	v_cvt_pk_bf16_f32 v8, v8, s0
	ds_write_b16 v2, v8 offset:2176
	v_mul_f32_e32 v8, v59, v9
	v_cvt_pk_bf16_f32 v8, v8, s0
	v_rcp_f32_e32 v11, v11
	ds_write_b16 v2, v8 offset:2240
	v_mul_f32_e32 v8, v44, v10
	v_cvt_pk_bf16_f32 v8, v8, s0
	ds_write_b16 v2, v8 offset:2304
	v_mul_f32_e32 v8, v60, v10
	v_cvt_pk_bf16_f32 v8, v8, s0
	s_waitcnt lgkmcnt(14)
	v_rcp_f32_e32 v12, v12
	ds_write_b16 v2, v8 offset:2368
	v_mul_f32_e32 v8, v45, v11
	v_cvt_pk_bf16_f32 v8, v8, s0
	ds_write_b16 v2, v8 offset:2432
	v_mul_f32_e32 v8, v61, v11
	v_cvt_pk_bf16_f32 v8, v8, s0
	v_rcp_f32_e32 v13, v13
	ds_write_b16 v2, v8 offset:2496
	v_mul_f32_e32 v8, v46, v12
	v_cvt_pk_bf16_f32 v8, v8, s0
	ds_write_b16 v2, v8 offset:3072
	v_mul_f32_e32 v8, v62, v12
	v_cvt_pk_bf16_f32 v8, v8, s0
	v_rcp_f32_e32 v14, v14
	ds_write_b16 v2, v8 offset:3136
	v_mul_f32_e32 v8, v47, v13
	v_cvt_pk_bf16_f32 v8, v8, s0
	ds_write_b16 v2, v8 offset:3200
	v_mul_f32_e32 v8, v63, v13
	v_cvt_pk_bf16_f32 v8, v8, s0
	v_rcp_f32_e32 v15, v15
	ds_write_b16 v2, v8 offset:3264
	v_mul_f32_e32 v8, v48, v14
	v_cvt_pk_bf16_f32 v8, v8, s0
	ds_write_b16 v2, v8 offset:3328
	v_mul_f32_e32 v8, v64, v14
	v_cvt_pk_bf16_f32 v8, v8, s0
	ds_write_b16 v2, v8 offset:3392
	v_mul_f32_e32 v8, v49, v15
	v_cvt_pk_bf16_f32 v8, v8, s0
	ds_write_b16 v2, v8 offset:3456
	v_mul_f32_e32 v8, v65, v15
	v_cvt_pk_bf16_f32 v26, v26, s0
	v_cvt_pk_bf16_f32 v20, v20, s0
	v_cvt_pk_bf16_f32 v16, v16, s0
	v_cvt_pk_bf16_f32 v8, v8, s0
	ds_write_b16 v2, v26
	ds_write_b16 v2, v20 offset:1280
	ds_write_b16 v2, v16 offset:2048
	ds_write_b16 v2, v8 offset:3520
	s_waitcnt lgkmcnt(0)
	ds_read_b128 v[8:11], v3
	ds_read_b128 v[12:15], v4
	s_ashr_i32 s3, s2, 31
	v_lshlrev_b32_e32 v0, 9, v71
	s_lshl_b64 s[2:3], s[2:3], 10
	v_lshlrev_b32_e32 v7, 9, v7
	v_lshl_add_u64 v[16:17], v[66:67], 0, s[2:3]
	v_lshlrev_b32_e32 v0, 1, v0
	v_lshl_add_u64 v[2:3], v[16:17], 0, v[0:1]
	v_lshlrev_b32_e32 v0, 1, v7
	s_waitcnt lgkmcnt(1)
	global_store_dwordx4 v[2:3], v[8:11], off
	ds_read_b128 v[2:5], v5
	s_cmp_gt_i32 s47, 11
	v_lshl_add_u64 v[8:9], v[16:17], 0, v[0:1]
	s_waitcnt lgkmcnt(1)
	global_store_dwordx4 v[8:9], v[12:15], off
	ds_read_b128 v[6:9], v6
	v_lshlrev_b32_e32 v0, 1, v18
	v_lshl_add_u64 v[10:11], v[16:17], 0, v[0:1]
	v_lshlrev_b32_e32 v0, 1, v19
	s_waitcnt lgkmcnt(1)
	global_store_dwordx4 v[10:11], v[2:5], off
	s_nop 1
	v_lshl_add_u64 v[2:3], v[16:17], 0, v[0:1]
	s_waitcnt lgkmcnt(0)
	global_store_dwordx4 v[2:3], v[6:9], off
	s_waitcnt lgkmcnt(0)
	s_waitcnt lgkmcnt(0)
	s_barrier
	s_cbranch_scc1 .LBB0_923
	v_readlane_b32 s2, v254, 26
	v_readlane_b32 s3, v254, 27
	s_mul_i32 s12, s47, s2
	v_readlane_b32 s2, v254, 22
	s_add_i32 s12, s12, s2
	v_readlane_b32 s3, v254, 23
	s_mul_hi_i32 s2, s12, 0x2fa0be83
	s_lshr_b32 s3, s2, 31
	s_ashr_i32 s6, s2, 11
	s_add_i32 s6, s6, s3
	s_mul_i32 s2, s6, 0x2b00
	s_sub_i32 s2, s12, s2
	s_mul_i32 s3, s2, 0x2fa1
	s_lshr_b32 s4, s3, 31
	s_ashr_i32 s7, s3, 23
	s_add_i32 s7, s7, s4
	s_mul_i32 s3, s7, 0x2b0
	s_sub_i32 s13, s2, s3
	s_cmpk_gt_i32 s12, 0x55ff
	s_mov_b64 s[4:5], -1
	v_mbcnt_lo_u32_b32 v2, -1, 0
	v_mbcnt_hi_u32_b32 v2, -1, v2
	s_cbranch_scc0 .LBB0_910
	s_and_b32 s2, 0xffff, s13
	s_lshl_b32 s3, s2, 6
	s_and_b32 s10, s3, 0x3c0
	s_lshl_b32 s4, s2, 2
	s_load_dwordx2 s[2:3], s[24:25], 0xc8
	s_and_b32 s11, s4, 0xfc0
	s_add_i32 s4, s67, s7
	s_mov_b32 s5, s87
	s_mul_i32 s4, s4, 0x2b0000
	s_lshl_b64 s[4:5], s[4:5], 2
	s_waitcnt lgkmcnt(0)
	s_add_u32 s2, s2, s4
	s_addc_u32 s3, s3, s5
	s_lshl_b32 s4, s7, 10
	s_or_b32 s4, s10, s4
	s_mulk_i32 s4, 0xb00
	s_add_u32 s4, s68, s4
	s_addc_u32 s5, s69, 0
	s_add_u32 s8, s4, s11
	s_addc_u32 s9, s5, 0
	s_lshl_b32 s4, s11, 12
	s_add_u32 s2, s2, s4
	s_addc_u32 s3, s3, 0
	s_lshl_b32 s4, s10, 2
	s_add_u32 s2, s2, s4
	s_addc_u32 s3, s3, 0
	v_lshlrev_b32_e32 v3, 4, v2
	v_lshlrev_b32_e32 v0, 8, v2
	v_and_b32_e32 v3, 0xf0, v3
	s_movk_i32 s4, 0xf000
	s_add_u32 s10, s8, 0x16000
	v_and_or_b32 v0, v0, s4, v3
	s_addc_u32 s11, s9, 0
	s_mov_b64 s[4:5], 0

; __device__ __forceinline__ const float* inp(CArgs a, int i) { return (const float*)(GAS const float*)a->in[i]; }
; __device__ __forceinline__ CvItem cv_make(CArgs a, unsigned char* ws, int l, int it, int lane) {
;     CvItem c; const int which = it / 11008, r = it % 11008, e = r / 688, q = r % 688;
;     if (which < 2) { const int kb = q / 43, nb = q % 43, n0 = nb * 64, k0 = kb * 64;
;         const float* W = inp(a, which == 0 ? I_WG : I_WU) + ((size_t)(l * NE + e) * D) * FF;
;         const int drow = e * 5632 + (n0 >> 7) * 256 + (n0 & 127) + which * 128; unsigned char* d0 = ws + WS_WGU + (size_t)drow * D + k0;
;         c.src = W + (size_t)k0 * FF + n0; c.voff = (unsigned)((lane >> 4) * FF + 4 * (lane & 15)) * 4u; c.ldw = FF; c.d0 = d0; c.d1 = d0 + (size_t)32 * D; c.pitch = D; c.scale = WSC_GU; }
;     else { const int kb = q / 16, nb = q % 16, n0 = nb * 64, k0 = kb * 64;
;         const float* W = inp(a, I_WDN) + ((size_t)(l * NE + e) * FF) * D; unsigned char* d0 = ws + WS_WD + ((size_t)e * D + n0) * FFP + k0;
;         c.src = W + (size_t)k0 * D + n0; c.voff = (unsigned)((lane >> 4) * D + 4 * (lane & 15)) * 4u; c.ldw = D; c.d0 = d0; c.d1 = d0 + (size_t)32 * FFP; c.pitch = FFP; c.scale = WSC_D; }
;     return c;
; }
.LBB0_913:
	s_cmp_lg_u32 s47, 11
	s_cselect_b64 s[6:7], -1, 0
	s_lshl_b32 s33, s4, 4
	s_add_u32 s4, s2, s33
	s_addc_u32 s5, s3, 0
	s_add_u32 s12, s4, s33
	s_addc_u32 s13, s5, 0
	s_add_u32 s14, s12, s33
	s_addc_u32 s15, s13, 0
	s_add_u32 s16, s14, s33
	s_addc_u32 s17, s15, 0
	s_add_u32 s20, s16, s33
	s_addc_u32 s21, s17, 0
	s_add_u32 s22, s20, s33
	s_addc_u32 s23, s21, 0
	s_add_u32 s34, s22, s33
	s_addc_u32 s35, s23, 0
	s_add_u32 s36, s34, s33
	s_addc_u32 s37, s35, 0
	s_add_u32 s38, s36, s33
	s_addc_u32 s39, s37, 0
	s_add_u32 s74, s38, s33
	s_addc_u32 s75, s39, 0
	s_add_u32 s76, s74, s33
	s_addc_u32 s77, s75, 0
	s_add_u32 s78, s76, s33
	s_addc_u32 s79, s77, 0
	s_add_u32 s80, s78, s33
	s_addc_u32 s81, s79, 0
	s_add_u32 s82, s80, s33
	s_addc_u32 s83, s81, 0
	s_add_u32 s84, s82, s33
	s_addc_u32 s85, s83, 0
	global_load_dwordx4 v[90:93], v0, s[2:3]
	global_load_dwordx4 v[114:117], v0, s[4:5]
	global_load_dwordx4 v[126:129], v0, s[12:13]
	global_load_dwordx4 v[102:105], v0, s[14:15]
	global_load_dwordx4 v[78:81], v0, s[16:17]
	global_load_dwordx4 v[106:109], v0, s[20:21]
	global_load_dwordx4 v[122:125], v0, s[22:23]
	global_load_dwordx4 v[94:97], v0, s[34:35]
	global_load_dwordx4 v[70:73], v0, s[36:37]
	global_load_dwordx4 v[98:101], v0, s[38:39]
	global_load_dwordx4 v[118:121], v0, s[74:75]
	global_load_dwordx4 v[82:85], v0, s[76:77]
	global_load_dwordx4 v[66:69], v0, s[78:79]
	global_load_dwordx4 v[86:89], v0, s[80:81]
	global_load_dwordx4 v[110:113], v0, s[82:83]
	global_load_dwordx4 v[74:77], v0, s[84:85]
	s_cmp_eq_u32 s47, 11
	s_waitcnt vmcnt(0)
	v_mov_b64_e32 v[62:63], v[74:75]
	v_mov_b64_e32 v[58:59], v[110:111]
	v_mov_b64_e32 v[54:55], v[86:87]
	v_mov_b64_e32 v[46:47], v[66:67]
	v_mov_b64_e32 v[50:51], v[82:83]
	v_mov_b64_e32 v[42:43], v[118:119]
	v_mov_b64_e32 v[38:39], v[98:99]
	v_mov_b64_e32 v[30:31], v[70:71]
	v_mov_b64_e32 v[34:35], v[94:95]
	v_mov_b64_e32 v[26:27], v[122:123]
	v_mov_b64_e32 v[22:23], v[106:107]
	v_mov_b64_e32 v[10:11], v[78:79]
	v_mov_b64_e32 v[18:19], v[102:103]
	v_mov_b64_e32 v[6:7], v[126:127]
	v_mov_b64_e32 v[2:3], v[90:91]
	v_mov_b64_e32 v[14:15], v[114:115]
	v_mov_b64_e32 v[64:65], v[76:77]
	v_mov_b64_e32 v[60:61], v[112:113]
	v_mov_b64_e32 v[56:57], v[88:89]
	v_mov_b64_e32 v[48:49], v[68:69]
	v_mov_b64_e32 v[52:53], v[84:85]
	v_mov_b64_e32 v[44:45], v[120:121]
	v_mov_b64_e32 v[40:41], v[100:101]
	v_mov_b64_e32 v[32:33], v[72:73]
	v_mov_b64_e32 v[36:37], v[96:97]
	v_mov_b64_e32 v[28:29], v[124:125]
	v_mov_b64_e32 v[24:25], v[108:109]
	v_mov_b64_e32 v[12:13], v[80:81]
	v_mov_b64_e32 v[20:21], v[104:105]
	v_mov_b64_e32 v[8:9], v[128:129]
	s_mov_b64 s[2:3], s[8:9]
	s_mov_b64 s[4:5], s[10:11]
	s_mov_b32 s16, s18
	s_mov_b32 s17, s19
	v_mov_b64_e32 v[4:5], v[92:93]
	v_mov_b64_e32 v[16:17], v[116:117]
	s_mov_b32 s33, 0x8000
	s_cbranch_scc1 .LBB0_920
	s_add_i32 s2, s47, 1
	v_readlane_b32 s4, v254, 26
	s_mul_i32 s20, s2, s4
	v_readlane_b32 s2, v254, 22
	s_add_i32 s20, s20, s2
	v_readlane_b32 s3, v254, 23
	s_mul_hi_i32 s2, s20, 0x2fa0be83
	s_lshr_b32 s3, s2, 31
	s_ashr_i32 s16, s2, 11
	s_add_i32 s16, s16, s3
	s_mul_i32 s2, s16, 0x2b00
	s_sub_i32 s2, s20, s2
	s_mul_i32 s3, s2, 0x2fa1
	s_lshr_b32 s4, s3, 31
	s_ashr_i32 s17, s3, 23
	s_add_i32 s17, s17, s4
	s_mul_i32 s3, s17, 0x2b0
	s_sub_i32 s21, s2, s3
	v_readlane_b32 s5, v254, 27
	s_cmpk_gt_i32 s20, 0x55ff
	s_mov_b64 s[14:15], -1
	v_mbcnt_lo_u32_b32 v2, -1, 0
	v_mbcnt_hi_u32_b32 v2, -1, v2
	s_cbranch_scc0 .LBB0_916
	s_and_b32 s2, 0xffff, s21
	s_lshl_b32 s3, s2, 6
	s_and_b32 s12, s3, 0x3c0
	s_lshl_b32 s4, s2, 2
	s_load_dwordx2 s[2:3], s[24:25], 0xc8
	s_and_b32 s13, s4, 0xfc0
	s_add_i32 s4, s67, s17
	s_mov_b32 s5, s87
	s_mul_i32 s4, s4, 0x2b0000
	s_lshl_b64 s[4:5], s[4:5], 2
	s_waitcnt lgkmcnt(0)
	s_add_u32 s4, s2, s4
	s_addc_u32 s5, s3, s5
	s_lshl_b32 s2, s17, 10
	s_or_b32 s2, s12, s2
	s_mulk_i32 s2, 0xb00
	s_add_u32 s2, s68, s2
	s_addc_u32 s3, s69, 0
	s_add_u32 s2, s2, s13
	s_addc_u32 s3, s3, 0
	s_lshl_b32 s13, s13, 12
	s_add_u32 s4, s4, s13
	s_addc_u32 s5, s5, 0
	s_lshl_b32 s12, s12, 2
	s_add_u32 s12, s4, s12
	v_lshlrev_b32_e32 v3, 4, v2
	s_addc_u32 s13, s5, 0
	v_lshlrev_b32_e32 v0, 8, v2
	v_and_b32_e32 v3, 0xf0, v3
	s_movk_i32 s4, 0xf000
	v_and_or_b32 v0, v0, s4, v3
	s_add_u32 s4, s2, 0x16000
	s_addc_u32 s5, s3, 0
	s_mov_b64 s[14:15], 0

; __device__ __forceinline__ const float* inp(CArgs a, int i) { return (const float*)(GAS const float*)a->in[i]; }
; __device__ __forceinline__ CvItem cv_make(CArgs a, unsigned char* ws, int l, int it, int lane) {
;     CvItem c; const int which = it / 11008, r = it % 11008, e = r / 688, q = r % 688;
;     if (which < 2) { const int kb = q / 43, nb = q % 43, n0 = nb * 64, k0 = kb * 64;
;         const float* W = inp(a, which == 0 ? I_WG : I_WU) + ((size_t)(l * NE + e) * D) * FF;
;         const int drow = e * 5632 + (n0 >> 7) * 256 + (n0 & 127) + which * 128; unsigned char* d0 = ws + WS_WGU + (size_t)drow * D + k0;
;         c.src = W + (size_t)k0 * FF + n0; c.voff = (unsigned)((lane >> 4) * FF + 4 * (lane & 15)) * 4u; c.ldw = FF; c.d0 = d0; c.d1 = d0 + (size_t)32 * D; c.pitch = D; c.scale = WSC_GU; }
;     else { const int kb = q / 16, nb = q % 16, n0 = nb * 64, k0 = kb * 64;
;         const float* W = inp(a, I_WDN) + ((size_t)(l * NE + e) * FF) * D; unsigned char* d0 = ws + WS_WD + ((size_t)e * D + n0) * FFP + k0;
;         c.src = W + (size_t)k0 * D + n0; c.voff = (unsigned)((lane >> 4) * D + 4 * (lane & 15)) * 4u; c.ldw = D; c.d0 = d0; c.d1 = d0 + (size_t)32 * FFP; c.pitch = FFP; c.scale = WSC_D; }
;     return c;
; }
.LBB0_923:
	s_cmp_gt_i32 s47, 11
	s_cbranch_scc1 .LBB0_716
	v_readlane_b32 s2, v254, 26
	v_readlane_b32 s3, v254, 27
	s_mul_i32 s12, s47, s2
	v_readlane_b32 s2, v254, 22
	s_add_i32 s12, s12, s2
	v_readlane_b32 s3, v254, 23
	s_mul_hi_i32 s2, s12, 0x2fa0be83
	s_lshr_b32 s3, s2, 31
	s_ashr_i32 s6, s2, 11
	s_add_i32 s6, s6, s3
	s_mul_i32 s2, s6, 0x2b00
	s_sub_i32 s2, s12, s2
	s_mul_i32 s3, s2, 0x2fa1
	s_lshr_b32 s4, s3, 31
	s_ashr_i32 s7, s3, 23
	s_add_i32 s7, s7, s4
	s_mul_i32 s3, s7, 0x2b0
	s_sub_i32 s13, s2, s3
	s_cmpk_gt_i32 s12, 0x55ff
	s_mov_b64 s[4:5], -1
	s_waitcnt vmcnt(19)
	v_mbcnt_lo_u32_b32 v2, -1, 0
	v_mbcnt_hi_u32_b32 v2, -1, v2
	s_cbranch_scc0 .LBB0_926
	s_and_b32 s2, 0xffff, s13
	s_lshl_b32 s3, s2, 6
	s_and_b32 s10, s3, 0x3c0
	s_lshl_b32 s4, s2, 2
	s_load_dwordx2 s[2:3], s[24:25], 0xc8
	s_and_b32 s11, s4, 0xfc0
	s_add_i32 s4, s67, s7
	s_mov_b32 s5, s87
	s_mul_i32 s4, s4, 0x2b0000
	s_lshl_b64 s[4:5], s[4:5], 2
	s_waitcnt lgkmcnt(0)
	s_add_u32 s2, s2, s4
	s_addc_u32 s3, s3, s5
	s_lshl_b32 s4, s7, 10
	s_or_b32 s4, s10, s4
	s_mulk_i32 s4, 0xb00
	s_add_u32 s4, s68, s4
	s_addc_u32 s5, s69, 0
	s_add_u32 s8, s4, s11
	s_addc_u32 s9, s5, 0
	s_lshl_b32 s4, s11, 12
	s_add_u32 s2, s2, s4
	s_addc_u32 s3, s3, 0
	s_lshl_b32 s4, s10, 2
	s_add_u32 s2, s2, s4
	s_addc_u32 s3, s3, 0
	v_lshlrev_b32_e32 v3, 4, v2
	v_lshlrev_b32_e32 v0, 8, v2
	v_and_b32_e32 v3, 0xf0, v3
	s_movk_i32 s4, 0xf000
	s_add_u32 s10, s8, 0x16000
	v_and_or_b32 v0, v0, s4, v3
	s_addc_u32 s11, s9, 0
	s_mov_b64 s[4:5], 0

; __device__ __forceinline__ const float* inp(CArgs a, int i) { return (const float*)(GAS const float*)a->in[i]; }
; __device__ __forceinline__ CvItem cv_make(CArgs a, unsigned char* ws, int l, int it, int lane) {
;     CvItem c; const int which = it / 11008, r = it % 11008, e = r / 688, q = r % 688;
;     if (which < 2) { const int kb = q / 43, nb = q % 43, n0 = nb * 64, k0 = kb * 64;
;         const float* W = inp(a, which == 0 ? I_WG : I_WU) + ((size_t)(l * NE + e) * D) * FF;
;         const int drow = e * 5632 + (n0 >> 7) * 256 + (n0 & 127) + which * 128; unsigned char* d0 = ws + WS_WGU + (size_t)drow * D + k0;
;         c.src = W + (size_t)k0 * FF + n0; c.voff = (unsigned)((lane >> 4) * FF + 4 * (lane & 15)) * 4u; c.ldw = FF; c.d0 = d0; c.d1 = d0 + (size_t)32 * D; c.pitch = D; c.scale = WSC_GU; }
;     else { const int kb = q / 16, nb = q % 16, n0 = nb * 64, k0 = kb * 64;
;         const float* W = inp(a, I_WDN) + ((size_t)(l * NE + e) * FF) * D; unsigned char* d0 = ws + WS_WD + ((size_t)e * D + n0) * FFP + k0;
;         c.src = W + (size_t)k0 * D + n0; c.voff = (unsigned)((lane >> 4) * D + 4 * (lane & 15)) * 4u; c.ldw = D; c.d0 = d0; c.d1 = d0 + (size_t)32 * FFP; c.pitch = FFP; c.scale = WSC_D; }
;     return c;
; }
.LBB0_929:
	s_cmp_lg_u32 s47, 11
	s_cselect_b64 s[6:7], -1, 0
	s_lshl_b32 s33, s4, 4
	s_add_u32 s4, s2, s33
	s_addc_u32 s5, s3, 0
	s_add_u32 s12, s4, s33
	s_addc_u32 s13, s5, 0
	s_add_u32 s14, s12, s33
	s_addc_u32 s15, s13, 0
	s_add_u32 s16, s14, s33
	s_addc_u32 s17, s15, 0
	s_add_u32 s20, s16, s33
	s_addc_u32 s21, s17, 0
	s_add_u32 s22, s20, s33
	s_addc_u32 s23, s21, 0
	s_add_u32 s34, s22, s33
	s_addc_u32 s35, s23, 0
	s_add_u32 s36, s34, s33
	s_addc_u32 s37, s35, 0
	s_add_u32 s38, s36, s33
	s_addc_u32 s39, s37, 0
	s_add_u32 s74, s38, s33
	s_addc_u32 s75, s39, 0
	s_add_u32 s76, s74, s33
	s_addc_u32 s77, s75, 0
	s_add_u32 s78, s76, s33
	s_addc_u32 s79, s77, 0
	s_add_u32 s80, s78, s33
	s_addc_u32 s81, s79, 0
	s_add_u32 s82, s80, s33
	s_addc_u32 s83, s81, 0
	s_add_u32 s84, s82, s33
	s_addc_u32 s85, s83, 0
	global_load_dwordx4 v[90:93], v0, s[2:3]
	global_load_dwordx4 v[114:117], v0, s[4:5]
	global_load_dwordx4 v[126:129], v0, s[12:13]
	global_load_dwordx4 v[102:105], v0, s[14:15]
	global_load_dwordx4 v[78:81], v0, s[16:17]
	global_load_dwordx4 v[106:109], v0, s[20:21]
	global_load_dwordx4 v[122:125], v0, s[22:23]
	global_load_dwordx4 v[94:97], v0, s[34:35]
	global_load_dwordx4 v[70:73], v0, s[36:37]
	global_load_dwordx4 v[98:101], v0, s[38:39]
	global_load_dwordx4 v[118:121], v0, s[74:75]
	global_load_dwordx4 v[82:85], v0, s[76:77]
	global_load_dwordx4 v[66:69], v0, s[78:79]
	global_load_dwordx4 v[86:89], v0, s[80:81]
	global_load_dwordx4 v[110:113], v0, s[82:83]
	global_load_dwordx4 v[74:77], v0, s[84:85]
	s_cmp_eq_u32 s47, 11
	s_waitcnt vmcnt(15)
	v_mov_b64_e32 v[2:3], v[90:91]
	s_waitcnt vmcnt(14)
	v_mov_b64_e32 v[6:7], v[114:115]
	s_waitcnt vmcnt(13)
	v_mov_b64_e32 v[10:11], v[126:127]
	s_waitcnt vmcnt(12)
	v_mov_b64_e32 v[18:19], v[102:103]
	s_waitcnt vmcnt(11)
	v_mov_b64_e32 v[14:15], v[78:79]
	s_waitcnt vmcnt(10)
	v_mov_b64_e32 v[22:23], v[106:107]
	s_waitcnt vmcnt(9)
	v_mov_b64_e32 v[26:27], v[122:123]
	s_waitcnt vmcnt(8)
	v_mov_b64_e32 v[34:35], v[94:95]
	s_waitcnt vmcnt(7)
	v_mov_b64_e32 v[30:31], v[70:71]
	s_waitcnt vmcnt(6)
	v_mov_b64_e32 v[38:39], v[98:99]
	s_waitcnt vmcnt(5)
	v_mov_b64_e32 v[42:43], v[118:119]
	s_waitcnt vmcnt(4)
	v_mov_b64_e32 v[50:51], v[82:83]
	s_waitcnt vmcnt(3)
	v_mov_b64_e32 v[46:47], v[66:67]
	s_waitcnt vmcnt(2)
	v_mov_b64_e32 v[54:55], v[86:87]
	s_waitcnt vmcnt(1)
	v_mov_b64_e32 v[58:59], v[110:111]
	s_waitcnt vmcnt(0)
	v_mov_b64_e32 v[62:63], v[74:75]
	s_mov_b64 s[2:3], s[8:9]
	s_mov_b64 s[4:5], s[10:11]
	s_mov_b32 s16, s18
	s_mov_b32 s17, s19
	v_mov_b64_e32 v[4:5], v[92:93]
	v_mov_b64_e32 v[8:9], v[116:117]
	v_mov_b64_e32 v[12:13], v[128:129]
	v_mov_b64_e32 v[20:21], v[104:105]
	v_mov_b64_e32 v[16:17], v[80:81]
	v_mov_b64_e32 v[24:25], v[108:109]
	v_mov_b64_e32 v[28:29], v[124:125]
	v_mov_b64_e32 v[36:37], v[96:97]
	v_mov_b64_e32 v[32:33], v[72:73]
	v_mov_b64_e32 v[40:41], v[100:101]
	v_mov_b64_e32 v[44:45], v[120:121]
	v_mov_b64_e32 v[52:53], v[84:85]
	v_mov_b64_e32 v[48:49], v[68:69]
	v_mov_b64_e32 v[56:57], v[88:89]
	v_mov_b64_e32 v[60:61], v[112:113]
	v_mov_b64_e32 v[64:65], v[76:77]
	s_cbranch_scc1 .LBB0_936
	s_add_i32 s2, s47, 1
	v_readlane_b32 s4, v254, 26
	s_mul_i32 s20, s2, s4
	v_readlane_b32 s2, v254, 22
	s_add_i32 s20, s20, s2
	v_readlane_b32 s3, v254, 23
	s_mul_hi_i32 s2, s20, 0x2fa0be83
	s_lshr_b32 s3, s2, 31
	s_ashr_i32 s16, s2, 11
	s_add_i32 s16, s16, s3
	s_mul_i32 s2, s16, 0x2b00
	s_sub_i32 s2, s20, s2
	s_mul_i32 s3, s2, 0x2fa1
	s_lshr_b32 s4, s3, 31
	s_ashr_i32 s17, s3, 23
	s_add_i32 s17, s17, s4
	s_mul_i32 s3, s17, 0x2b0
	s_sub_i32 s21, s2, s3
	v_readlane_b32 s5, v254, 27
	s_cmpk_gt_i32 s20, 0x55ff
	s_mov_b64 s[14:15], -1
	v_mbcnt_lo_u32_b32 v2, -1, 0
	v_mbcnt_hi_u32_b32 v2, -1, v2
	s_cbranch_scc0 .LBB0_932
	s_and_b32 s2, 0xffff, s21
	s_lshl_b32 s3, s2, 6
	s_and_b32 s12, s3, 0x3c0
	s_lshl_b32 s4, s2, 2
	s_load_dwordx2 s[2:3], s[24:25], 0xc8
	s_and_b32 s13, s4, 0xfc0
	s_add_i32 s4, s67, s17
	s_mov_b32 s5, s87
	s_mul_i32 s4, s4, 0x2b0000
	s_lshl_b64 s[4:5], s[4:5], 2
	s_waitcnt lgkmcnt(0)
	s_add_u32 s4, s2, s4
	s_addc_u32 s5, s3, s5
	s_lshl_b32 s2, s17, 10
	s_or_b32 s2, s12, s2
	s_mulk_i32 s2, 0xb00
	s_add_u32 s2, s68, s2
	s_addc_u32 s3, s69, 0
	s_add_u32 s2, s2, s13
	s_addc_u32 s3, s3, 0
	s_lshl_b32 s13, s13, 12
	s_add_u32 s4, s4, s13
	s_addc_u32 s5, s5, 0
	s_lshl_b32 s12, s12, 2
	s_add_u32 s12, s4, s12
	v_lshlrev_b32_e32 v3, 4, v2
	s_addc_u32 s13, s5, 0
	v_lshlrev_b32_e32 v0, 8, v2
	v_and_b32_e32 v3, 0xf0, v3
	s_movk_i32 s4, 0xf000
	v_and_or_b32 v0, v0, s4, v3
	s_add_u32 s4, s2, 0x16000
	s_addc_u32 s5, s3, 0
	s_mov_b64 s[14:15], 0

; __device__ __forceinline__ void ph_attention(const Ctx& X, CArgs a, int l, unsigned char* lds_generic, bool need_ctx) {
;     ...
;         ATT_CV();
;     }
;     while (cvk < CV_IN_ATT) ATT_CV();
.LBB0_966:
	v_readlane_b32 s42, v254, 55
	s_cmp_gt_i32 s47, 11
	v_readlane_b32 s34, v254, 26
	v_readlane_b32 s43, v254, 56
	v_readlane_b32 s35, v254, 27
	s_cbranch_scc1 .LBB0_983
	v_readlane_b32 s2, v254, 53
	s_lshl_b32 s16, s2, 4
	s_add_u32 s17, s26, 0xda40000
	s_addc_u32 s18, s27, 0
	s_add_u32 s19, s26, 0x2a40000
	v_readlane_b32 s3, v254, 54
	s_addc_u32 s20, s27, 0
	s_add_i32 s2, s47, 1
	s_mul_i32 s2, s34, s2
	v_readlane_b32 s3, v253, 10
	s_add_i32 s21, s3, s2
	s_mul_i32 s2, s34, s47
	s_add_i32 s22, s47, -2
	s_add_i32 s23, s3, s2
	s_branch .LBB0_969
.LBB0_968:
	v_readlane_b32 s2, v254, 49
	s_add_i32 s21, s21, s2
	s_add_i32 s22, s22, 2
	s_add_i32 s23, s23, s2
	s_cmp_lt_i32 s22, 10
	v_readlane_b32 s3, v254, 50
	s_cbranch_scc0 .LBB0_983

; __device__ __forceinline__ void cv_load(f32x4 (&v)[16], const CvItem& c) {
; #pragma unroll
;     for (int i = 0; i < 16; ++i) v[i] = *(const f32x4*)((const char*)uni(c.src + (size_t)(4 * i) * c.ldw) + c.voff);
; }
.LBB0_974:
	s_cmp_lg_u32 s22, 9
	s_cselect_b64 s[6:7], -1, 0
	s_lshl_b32 s33, s4, 4
	s_add_u32 s4, s2, s33
	s_addc_u32 s5, s3, 0
	s_add_u32 s12, s4, s33
	s_addc_u32 s13, s5, 0
	s_add_u32 s14, s12, s33
	s_addc_u32 s15, s13, 0
	s_add_u32 s26, s14, s33
	s_addc_u32 s27, s15, 0
	s_add_u32 s30, s26, s33
	s_addc_u32 s31, s27, 0
	s_add_u32 s34, s30, s33
	s_addc_u32 s35, s31, 0
	s_add_u32 s36, s34, s33
	s_addc_u32 s37, s35, 0
	s_add_u32 s38, s36, s33
	s_addc_u32 s39, s37, 0
	s_add_u32 s40, s38, s33
	s_addc_u32 s41, s39, 0
	s_add_u32 s42, s40, s33
	s_addc_u32 s43, s41, 0
	s_add_u32 s44, s42, s33
	s_addc_u32 s45, s43, 0
	s_add_u32 s46, s44, s33
	s_addc_u32 s47, s45, 0
	s_add_u32 s48, s46, s33
	s_addc_u32 s49, s47, 0
	s_add_u32 s50, s48, s33
	s_addc_u32 s51, s49, 0
	s_add_u32 s52, s50, s33
	s_addc_u32 s53, s51, 0
	global_load_dwordx4 v[90:93], v0, s[2:3]
	global_load_dwordx4 v[114:117], v0, s[4:5]
	global_load_dwordx4 v[126:129], v0, s[12:13]
	global_load_dwordx4 v[102:105], v0, s[14:15]
	global_load_dwordx4 v[78:81], v0, s[26:27]
	global_load_dwordx4 v[106:109], v0, s[30:31]
	global_load_dwordx4 v[122:125], v0, s[34:35]
	global_load_dwordx4 v[94:97], v0, s[36:37]
	global_load_dwordx4 v[70:73], v0, s[38:39]
	global_load_dwordx4 v[98:101], v0, s[40:41]
	global_load_dwordx4 v[118:121], v0, s[42:43]
	global_load_dwordx4 v[82:85], v0, s[44:45]
	global_load_dwordx4 v[66:69], v0, s[46:47]
	global_load_dwordx4 v[86:89], v0, s[48:49]
	global_load_dwordx4 v[110:113], v0, s[50:51]
	global_load_dwordx4 v[74:77], v0, s[52:53]
	s_cmp_eq_u32 s22, 9
	s_waitcnt vmcnt(15)
	v_mov_b64_e32 v[2:3], v[90:91]
	s_waitcnt vmcnt(14)
	v_mov_b64_e32 v[6:7], v[114:115]
	s_waitcnt vmcnt(13)
	v_mov_b64_e32 v[10:11], v[126:127]
	s_waitcnt vmcnt(12)
	v_mov_b64_e32 v[18:19], v[102:103]
	s_waitcnt vmcnt(11)
	v_mov_b64_e32 v[14:15], v[78:79]
	s_waitcnt vmcnt(10)
	v_mov_b64_e32 v[22:23], v[106:107]
	s_waitcnt vmcnt(9)
	v_mov_b64_e32 v[26:27], v[122:123]
	s_waitcnt vmcnt(8)
	v_mov_b64_e32 v[34:35], v[94:95]
	s_waitcnt vmcnt(7)
	v_mov_b64_e32 v[30:31], v[70:71]
	s_waitcnt vmcnt(6)
	v_mov_b64_e32 v[38:39], v[98:99]
	s_waitcnt vmcnt(5)
	v_mov_b64_e32 v[42:43], v[118:119]
	s_waitcnt vmcnt(4)
	v_mov_b64_e32 v[50:51], v[82:83]
	s_waitcnt vmcnt(3)
	v_mov_b64_e32 v[46:47], v[66:67]
	s_waitcnt vmcnt(2)
	v_mov_b64_e32 v[54:55], v[86:87]
	s_waitcnt vmcnt(1)
	v_mov_b64_e32 v[58:59], v[110:111]
	s_waitcnt vmcnt(0)
	v_mov_b64_e32 v[62:63], v[74:75]
	v_readlane_b32 s42, v254, 55
	s_mov_b64 s[2:3], s[8:9]
	s_mov_b64 s[4:5], s[10:11]
	s_mov_b32 s26, s28
	s_mov_b32 s27, s29
	v_mov_b64_e32 v[4:5], v[92:93]
	v_mov_b64_e32 v[8:9], v[116:117]
	v_mov_b64_e32 v[12:13], v[128:129]
	v_mov_b64_e32 v[20:21], v[104:105]
	v_mov_b64_e32 v[16:17], v[80:81]
	v_mov_b64_e32 v[24:25], v[108:109]
	v_mov_b64_e32 v[28:29], v[124:125]
	v_mov_b64_e32 v[36:37], v[96:97]
	v_mov_b64_e32 v[32:33], v[72:73]
	v_mov_b64_e32 v[40:41], v[100:101]
	v_mov_b64_e32 v[44:45], v[120:121]
	v_mov_b64_e32 v[52:53], v[84:85]
	v_mov_b64_e32 v[48:49], v[68:69]
	v_mov_b64_e32 v[56:57], v[88:89]
	v_mov_b64_e32 v[60:61], v[112:113]
	v_mov_b64_e32 v[64:65], v[76:77]
	v_readlane_b32 s34, v254, 26
	v_readlane_b32 s43, v254, 56
	v_readlane_b32 s35, v254, 27
	s_cbranch_scc1 .LBB0_981
	v_readlane_b32 s2, v253, 11
	s_add_i32 s30, s2, s21
	s_mul_hi_i32 s2, s30, 0x2fa0be83
	s_lshr_b32 s3, s2, 31
	s_ashr_i32 s26, s2, 11
	s_add_i32 s26, s26, s3
	s_mul_i32 s2, s26, 0x2b00
	s_sub_i32 s2, s30, s2
	s_mul_i32 s3, s2, 0x2fa1
	s_lshr_b32 s4, s3, 31
	s_ashr_i32 s27, s3, 23
	s_add_i32 s27, s27, s4
	s_mul_i32 s3, s27, 0x2b0
	s_sub_i32 s31, s2, s3
	s_cmpk_gt_i32 s30, 0x55ff
	s_mov_b64 s[14:15], -1
	v_mbcnt_lo_u32_b32 v2, -1, 0
	v_mbcnt_hi_u32_b32 v2, -1, v2
	s_cbranch_scc0 .LBB0_977
	s_and_b32 s2, 0xffff, s31
	s_lshl_b32 s3, s2, 6
	s_and_b32 s12, s3, 0x3c0
	s_lshl_b32 s4, s2, 2
	s_load_dwordx2 s[2:3], s[24:25], 0xc8
	s_and_b32 s13, s4, 0xfc0
	s_add_i32 s4, s16, s27
	s_mul_i32 s86, s4, 0x2b0000
	s_lshl_b64 s[4:5], s[86:87], 2
	s_waitcnt lgkmcnt(0)
	s_add_u32 s4, s2, s4
	s_addc_u32 s5, s3, s5
	s_lshl_b32 s2, s27, 10
	s_or_b32 s2, s12, s2
	s_mulk_i32 s2, 0xb00
	s_add_u32 s2, s17, s2
	s_addc_u32 s3, s18, 0
	s_add_u32 s2, s2, s13
	s_addc_u32 s3, s3, 0
	s_lshl_b32 s13, s13, 12
	s_add_u32 s4, s4, s13
	s_addc_u32 s5, s5, 0
	s_lshl_b32 s12, s12, 2
	s_add_u32 s12, s4, s12
	v_lshlrev_b32_e32 v3, 4, v2
	s_addc_u32 s13, s5, 0
	v_lshlrev_b32_e32 v0, 8, v2
	v_and_b32_e32 v3, 0xf0, v3
	s_movk_i32 s4, 0xf000
	v_and_or_b32 v0, v0, s4, v3
	s_add_u32 s4, s2, 0x16000
	s_addc_u32 s5, s3, 0
	s_mov_b64 s[14:15], 0

; #define LAS __attribute__((address_space(3)))
; __device__ __forceinline__ void ph_topk_convert(const Ctx& X, CArgs a, int l, bool need_ctx) {
;     ...
;     LAS bf16* scr = (LAS bf16*)(X.lds + 32768 + X.wave * 8448);
;     const int gw = X.vcu * NWAVES + X.wave, NGW = X.G * NWAVES;
;     unsigned char* WGU = X.ws + WS_WGU; unsigned char* WD = X.ws + WS_WD;
;     __syncthreads();
;     for (int it = gw + CV_IN_ATT * NGW; it < CV_ITEMS; it += NGW) {
;         const CvItem ci = cv_make(a, X.ws, l, it, X.lane); f32x4 v[16]; unsigned P[4][4]; cv_load(v, ci); cv_pack8(v, ci.scale, P); cv_store8(P, ci, X.lane); }
.LBB0_2098:
	v_readlane_b32 s4, v254, 19
	s_add_u32 s2, s24, 0x2a40000
	v_readlane_b32 s5, v254, 20
	s_addc_u32 s3, s25, 0
	s_andn2_b64 vcc, exec, s[4:5]
	v_readlane_b32 s57, v253, 12
	s_barrier
	v_readlane_b32 s4, v254, 53
	s_lshl_b32 s16, s4, 4
	v_lshlrev_b32_e32 v0, 8, v66
	v_lshlrev_b32_e32 v2, 4, v66
	s_movk_i32 s4, 0x30f0
	v_bitop3_b32 v67, v0, s4, v2 bitop3:0xc8
	v_lshrrev_b32_e32 v2, 4, v66
	v_and_b32_e32 v0, 60, v12
	v_mul_u32_u24_e32 v3, 0xac0, v2
	v_readlane_b32 s5, v254, 54
	v_or_b32_e32 v3, v3, v0
	v_or_b32_e32 v2, v0, v2
	s_add_u32 s17, s24, 0xda40000
	v_lshlrev_b32_e32 v68, 2, v3
	v_subrev_u32_e32 v3, 32, v2
	v_cmp_gt_u32_e64 s[4:5], 32, v0
	s_addc_u32 s18, s25, 0
	v_readlane_b32 s19, v253, 2
	s_and_b64 s[100:101], s[92:93], exec
	s_cselect_b32 s100, 0x80, 0x40
	s_sub_i32 s101, s57, s100
	s_cmp_gt_i32 s101, 0
	s_cbranch_scc1 .Lmy_cvs_idle
	v_readlane_b32 s19, v254, 22
	v_readlane_b32 s101, v254, 26
	s_nop 3
	s_mul_i32 s100, s101, 12
	s_add_i32 s19, s19, s100
	s_cmp_gt_i32 s19, 0x80ff
	s_cbranch_scc1 .LBB0_2106
	s_branch .Lmy_cvs_go
.Lmy_cvs_idle:
	s_sub_i32 s19, s19, s100
	s_cmp_lt_i32 s19, 0
	s_cbranch_scc1 .LBB0_2106
	s_lshl_b32 s101, s101, 3
	v_readlane_b32 s100, v253, 6
	s_lshl_b32 s19, s19, 3
	s_nop 2
	s_lshr_b32 s100, s100, 6
	s_add_i32 s19, s19, s100
	v_readlane_b32 s100, v254, 26
	s_nop 3
	s_mul_i32 s100, s100, 12
	s_add_i32 s19, s19, s100
	s_cmp_gt_i32 s19, 0x80ff
	s_cbranch_scc1 .LBB0_2106
.Lmy_cvs_go:
	v_cndmask_b32_e64 v0, v3, v2, s[4:5]
	s_branch .LBB0_2102

; __device__ __forceinline__ unsigned pk_fp8x4(float a, float b, float c, float d) { int w = 0; w = __builtin_amdgcn_cvt_pk_fp8_f32(clamp448(a), clamp448(b), w, false); w = __builtin_amdgcn_cvt_pk_fp8_f32(clamp448(c), clamp448(d), w, true); return (unsigned)w; }
; __device__ __forceinline__ void cv_pack8(const f32x4 (&v)[16], float scale, unsigned (&P)[4][4]) {
; #pragma unroll
;     for (int j = 0; j < 4; ++j)
; #pragma unroll
;         for (int g = 0; g < 4; ++g) P[j][g] = pg8::pk_fp8x4(v[4 * g][j] * scale, v[4 * g + 1][j] * scale, v[4 * g + 2][j] * scale, v[4 * g + 3][j] * scale);
; }
; __device__ __forceinline__ void ph_topk_convert(const Ctx& X, CArgs a, int l, bool need_ctx) {
;     ...
;     for (int it = gw + CV_IN_ATT * NGW; it < CV_ITEMS; it += NGW) {
;         const CvItem ci = cv_make(a, X.ws, l, it, X.lane); f32x4 v[16]; unsigned P[4][4]; cv_load(v, ci); cv_pack8(v, ci.scale, P); cv_store8(P, ci, X.lane); }
.LBB0_2101:
	s_lshl_b32 s11, s14, 4
	global_load_dwordx4 v[6:9], v62, s[12:13]
	s_add_u32 s12, s12, s11
	s_addc_u32 s13, s13, 0
	global_load_dwordx4 v[14:17], v62, s[12:13]
	s_add_u32 s12, s12, s11
	s_addc_u32 s13, s13, 0
	global_load_dwordx4 v[22:25], v62, s[12:13]
	s_add_u32 s12, s12, s11
	s_addc_u32 s13, s13, 0
	global_load_dwordx4 v[38:41], v62, s[12:13]
	s_add_u32 s12, s12, s11
	s_addc_u32 s13, s13, 0
	global_load_dwordx4 v[10:13], v62, s[12:13]
	s_add_u32 s12, s12, s11
	s_addc_u32 s13, s13, 0
	global_load_dwordx4 v[18:21], v62, s[12:13]
	s_add_u32 s12, s12, s11
	s_addc_u32 s13, s13, 0
	global_load_dwordx4 v[26:29], v62, s[12:13]
	s_add_u32 s12, s12, s11
	s_addc_u32 s13, s13, 0
	global_load_dwordx4 v[42:45], v62, s[12:13]
	s_add_u32 s12, s12, s11
	s_addc_u32 s13, s13, 0
	global_load_dwordx4 v[2:5], v62, s[12:13]
	s_add_u32 s12, s12, s11
	s_addc_u32 s13, s13, 0
	global_load_dwordx4 v[30:33], v62, s[12:13]
	s_add_u32 s12, s12, s11
	s_addc_u32 s13, s13, 0
	global_load_dwordx4 v[46:49], v62, s[12:13]
	s_add_u32 s12, s12, s11
	s_addc_u32 s13, s13, 0
	global_load_dwordx4 v[54:57], v62, s[12:13]
	s_add_u32 s12, s12, s11
	s_addc_u32 s13, s13, 0
	global_load_dwordx4 v[34:37], v62, s[12:13]
	s_add_u32 s12, s12, s11
	s_addc_u32 s13, s13, 0
	global_load_dwordx4 v[50:53], v62, s[12:13]
	s_add_u32 s12, s12, s11
	s_addc_u32 s13, s13, 0
	global_load_dwordx4 v[58:61], v62, s[12:13]
	s_add_u32 s12, s12, s11
	s_addc_u32 s13, s13, 0
	global_load_dwordx4 v[62:65], v62, s[12:13]
	s_add_i32 s19, s19, s101
	s_cmp_gt_i32 s19, 0x80ff
	s_waitcnt vmcnt(15)
	v_mul_f32_e32 v6, s20, v6
	v_med3_f32 v69, v6, s59, v250
	v_mov_b32_e32 v6, v1
	s_waitcnt vmcnt(14)
	v_mul_f32_e32 v14, s20, v14
	v_med3_f32 v14, v14, s59, v250
	v_cvt_pk_fp8_f32 v6, v69, v14
	s_waitcnt vmcnt(13)
	v_mul_f32_e32 v22, s20, v22
	v_med3_f32 v14, v22, s59, v250
	v_mul_f32_e32 v7, s20, v7
	s_waitcnt vmcnt(12)
	v_mul_f32_e32 v38, s20, v38
	v_med3_f32 v22, v38, s59, v250
	v_cvt_pk_fp8_f32 v6, v14, v22 op_sel:[0,0,1]
	s_waitcnt vmcnt(11)
	v_mul_f32_e32 v10, s20, v10
	v_mul_f32_e32 v15, s20, v15
	v_med3_f32 v7, v7, s59, v250
	s_waitcnt vmcnt(10)
	v_mul_f32_e32 v14, s20, v18
	v_med3_f32 v14, v14, s59, v250
	v_med3_f32 v15, v15, s59, v250
	s_waitcnt vmcnt(9)
	v_mul_f32_e32 v18, s20, v26
	v_med3_f32 v26, v10, s59, v250
	v_mov_b32_e32 v10, v1
	v_cvt_pk_fp8_f32 v10, v26, v14
	s_waitcnt vmcnt(8)
	v_mul_f32_e32 v22, s20, v42
	v_med3_f32 v14, v18, s59, v250
	v_med3_f32 v18, v22, s59, v250
	v_cvt_pk_fp8_f32 v10, v14, v18 op_sel:[0,0,1]
	s_waitcnt vmcnt(7)
	v_mul_f32_e32 v2, s20, v2
	s_waitcnt vmcnt(6)
	v_mul_f32_e32 v14, s20, v30
	v_med3_f32 v26, v2, s59, v250
	v_med3_f32 v14, v14, s59, v250
	v_mov_b32_e32 v2, v1
	v_cvt_pk_fp8_f32 v2, v26, v14
	s_waitcnt vmcnt(5)
	v_mul_f32_e32 v18, s20, v46
	s_waitcnt vmcnt(4)
	v_mul_f32_e32 v22, s20, v54
	v_med3_f32 v14, v18, s59, v250
	v_med3_f32 v18, v22, s59, v250
	v_cvt_pk_fp8_f32 v2, v14, v18 op_sel:[0,0,1]
	s_waitcnt vmcnt(3)
	v_mul_f32_e32 v14, s20, v34
	v_med3_f32 v30, v14, s59, v250
	s_waitcnt vmcnt(2)
	v_mul_f32_e32 v18, s20, v50
	v_med3_f32 v18, v18, s59, v250
	v_mov_b32_e32 v14, v1
	v_cvt_pk_fp8_f32 v14, v30, v18
	s_waitcnt vmcnt(1)
	v_mul_f32_e32 v22, s20, v58
	v_med3_f32 v18, v22, s59, v250
	s_waitcnt vmcnt(0)
; #define GAS __attribute__((address_space(1)))
; __device__ __forceinline__ unsigned pk_fp8x4(float a, float b, float c, float d) { int w = 0; w = __builtin_amdgcn_cvt_pk_fp8_f32(clamp448(a), clamp448(b), w, false); w = __builtin_amdgcn_cvt_pk_fp8_f32(clamp448(c), clamp448(d), w, true); return (unsigned)w; }
; __device__ __forceinline__ void cv_pack8(const f32x4 (&v)[16], float scale, unsigned (&P)[4][4]) {
; #pragma unroll
;     for (int j = 0; j < 4; ++j)
; #pragma unroll
;         for (int g = 0; g < 4; ++g) P[j][g] = pg8::pk_fp8x4(v[4 * g][j] * scale, v[4 * g + 1][j] * scale, v[4 * g + 2][j] * scale, v[4 * g + 3][j] * scale);
; }
; __device__ __forceinline__ void cv_store8(const unsigned (&P)[4][4], const CvItem& ci, int lane) {
;     const int n = 4 * (lane & 15) + (lane >> 4);
;     unsigned char* d = (n < 32) ? ci.d0 + (size_t)n * ci.pitch : ci.d1 + (size_t)(n - 32) * ci.pitch;
; #pragma unroll
;     for (int g = 0; g < 4; ++g) {
;         const auto a = __builtin_amdgcn_permlane16_swap(P[0][g], P[1][g], false, false); const auto b = __builtin_amdgcn_permlane16_swap(P[2][g], P[3][g], false, false);
;         const auto c = __builtin_amdgcn_permlane32_swap(a[0], b[0], false, false); const auto e = __builtin_amdgcn_permlane32_swap(a[1], b[1], false, false);
;         const unsigned q0 = c[0], q2 = c[1], q1 = e[0], q3 = e[1];
;         const unsigned t0 = __builtin_amdgcn_perm(q1, q0, 0x05010400u), t1 = __builtin_amdgcn_perm(q1, q0, 0x07030602u), t2 = __builtin_amdgcn_perm(q3, q2, 0x05010400u), t3 = __builtin_amdgcn_perm(q3, q2, 0x07030602u);
;         v4u o; o.x = __builtin_amdgcn_perm(t2, t0, 0x05040100u); o.y = __builtin_amdgcn_perm(t2, t0, 0x07060302u); o.z = __builtin_amdgcn_perm(t3, t1, 0x05040100u); o.w = __builtin_amdgcn_perm(t3, t1, 0x07060302u);
;         *(GAS v4u*)(d + 16 * g) = o; }
; }
	v_mul_f32_e32 v26, s20, v62
	v_med3_f32 v22, v26, s59, v250
	v_cvt_pk_fp8_f32 v14, v18, v22 op_sel:[0,0,1]
	v_mul_f32_e32 v18, s20, v23
	v_mov_b32_e32 v23, v1
	v_cvt_pk_fp8_f32 v23, v7, v15
	v_mul_f32_e32 v22, s20, v39
	v_med3_f32 v7, v18, s59, v250
	v_med3_f32 v15, v22, s59, v250
	v_cvt_pk_fp8_f32 v23, v7, v15 op_sel:[0,0,1]
	v_mul_f32_e32 v7, s20, v11
	v_mul_f32_e32 v11, s20, v19
	v_med3_f32 v7, v7, s59, v250
	v_med3_f32 v11, v11, s59, v250
	v_mov_b32_e32 v19, v1
	v_cvt_pk_fp8_f32 v19, v7, v11
	v_mul_f32_e32 v15, s20, v27
	v_mul_f32_e32 v18, s20, v43
	v_med3_f32 v7, v15, s59, v250
	v_med3_f32 v11, v18, s59, v250
	v_cvt_pk_fp8_f32 v19, v7, v11 op_sel:[0,0,1]
	v_mul_f32_e32 v3, s20, v3
	v_mul_f32_e32 v7, s20, v31
	v_med3_f32 v3, v3, s59, v250
	v_med3_f32 v7, v7, s59, v250
	v_mov_b32_e32 v18, v1
	v_cvt_pk_fp8_f32 v18, v3, v7
	v_mul_f32_e32 v11, s20, v47
	v_mul_f32_e32 v15, s20, v55
	v_med3_f32 v3, v11, s59, v250
	v_med3_f32 v7, v15, s59, v250
	v_cvt_pk_fp8_f32 v18, v3, v7 op_sel:[0,0,1]
	v_mul_f32_e32 v3, s20, v35
	v_mul_f32_e32 v7, s20, v51
	v_med3_f32 v3, v3, s59, v250
	v_med3_f32 v7, v7, s59, v250
	v_mov_b32_e32 v22, v1
	v_cvt_pk_fp8_f32 v22, v3, v7
	v_mul_f32_e32 v11, s20, v59
	v_mul_f32_e32 v15, s20, v63
	v_med3_f32 v3, v11, s59, v250
	v_med3_f32 v7, v15, s59, v250
	v_cvt_pk_fp8_f32 v22, v3, v7 op_sel:[0,0,1]
	v_mul_f32_e32 v3, s20, v8
	v_mul_f32_e32 v7, s20, v16
	v_med3_f32 v3, v3, s59, v250
	v_med3_f32 v7, v7, s59, v250
	v_mov_b32_e32 v15, v1
	v_cvt_pk_fp8_f32 v15, v3, v7
	v_mul_f32_e32 v8, s20, v24
	v_mul_f32_e32 v11, s20, v40
	v_med3_f32 v3, v8, s59, v250
	v_med3_f32 v7, v11, s59, v250
	v_cvt_pk_fp8_f32 v15, v3, v7 op_sel:[0,0,1]
	v_mul_f32_e32 v3, s20, v12
	v_mul_f32_e32 v7, s20, v20
	v_med3_f32 v3, v3, s59, v250
	v_med3_f32 v7, v7, s59, v250
	v_mov_b32_e32 v12, v1
	v_cvt_pk_fp8_f32 v12, v3, v7
	v_mul_f32_e32 v8, s20, v28
	v_mul_f32_e32 v11, s20, v44
	v_med3_f32 v3, v8, s59, v250
	v_med3_f32 v7, v11, s59, v250
	v_cvt_pk_fp8_f32 v12, v3, v7 op_sel:[0,0,1]
	v_mul_f32_e32 v3, s20, v4
	v_mul_f32_e32 v4, s20, v32
	v_med3_f32 v3, v3, s59, v250
	v_med3_f32 v4, v4, s59, v250
	v_mov_b32_e32 v11, v1
	v_cvt_pk_fp8_f32 v11, v3, v4
	v_mul_f32_e32 v7, s20, v48
	v_mul_f32_e32 v8, s20, v56
	v_med3_f32 v3, v7, s59, v250
	v_med3_f32 v4, v8, s59, v250
	v_cvt_pk_fp8_f32 v11, v3, v4 op_sel:[0,0,1]
	v_mul_f32_e32 v3, s20, v36
	v_mul_f32_e32 v4, s20, v52
	v_med3_f32 v3, v3, s59, v250
	v_med3_f32 v4, v4, s59, v250
	v_mov_b32_e32 v16, v1
	v_cvt_pk_fp8_f32 v16, v3, v4
	v_mul_f32_e32 v7, s20, v60
	v_mul_f32_e32 v8, s20, v64
	v_med3_f32 v3, v7, s59, v250
	v_med3_f32 v4, v8, s59, v250
	v_cvt_pk_fp8_f32 v16, v3, v4 op_sel:[0,0,1]
	v_mul_f32_e32 v3, s20, v9
	v_mul_f32_e32 v4, s20, v17
	v_med3_f32 v3, v3, s59, v250
	v_med3_f32 v4, v4, s59, v250
	v_mov_b32_e32 v17, v1
	v_cvt_pk_fp8_f32 v17, v3, v4
	v_mul_f32_e32 v7, s20, v25
	v_mul_f32_e32 v8, s20, v41
	v_med3_f32 v3, v7, s59, v250
	v_med3_f32 v4, v8, s59, v250
	v_cvt_pk_fp8_f32 v17, v3, v4 op_sel:[0,0,1]
	v_mul_f32_e32 v3, s20, v13
	v_mul_f32_e32 v4, s20, v21
	v_med3_f32 v3, v3, s59, v250
	v_med3_f32 v4, v4, s59, v250
	v_mov_b32_e32 v13, v1
	v_cvt_pk_fp8_f32 v13, v3, v4
	v_mul_f32_e32 v7, s20, v29
	v_mul_f32_e32 v8, s20, v45
	v_med3_f32 v3, v7, s59, v250
	v_med3_f32 v4, v8, s59, v250
	v_cvt_pk_fp8_f32 v13, v3, v4 op_sel:[0,0,1]
	v_mul_f32_e32 v3, s20, v5
	v_mul_f32_e32 v4, s20, v33
	v_med3_f32 v3, v3, s59, v250
	v_med3_f32 v4, v4, s59, v250
	v_mov_b32_e32 v20, v1
	v_cvt_pk_fp8_f32 v20, v3, v4
	v_mul_f32_e32 v5, s20, v49
	v_mul_f32_e32 v7, s20, v57
	v_med3_f32 v3, v5, s59, v250
	v_med3_f32 v4, v7, s59, v250
	v_cvt_pk_fp8_f32 v20, v3, v4 op_sel:[0,0,1]
	v_mul_f32_e32 v3, s20, v37
	v_mul_f32_e32 v4, s20, v53
	v_med3_f32 v3, v3, s59, v250
	v_med3_f32 v4, v4, s59, v250
	v_mov_b32_e32 v21, v1
	v_cvt_pk_fp8_f32 v21, v3, v4
	v_mul_f32_e32 v5, s20, v61
	v_mul_f32_e32 v7, s20, v65
	v_med3_f32 v3, v5, s59, v250
	v_med3_f32 v4, v7, s59, v250
	v_cvt_pk_fp8_f32 v21, v3, v4 op_sel:[0,0,1]
	v_mov_b32_e32 v3, s9
	v_mov_b32_e32 v4, s7
	v_cndmask_b32_e64 v5, v3, v4, s[4:5]
	v_mov_b32_e32 v3, s8
	v_mov_b32_e32 v4, s6
	v_cndmask_b32_e64 v4, v3, v4, s[4:5]
	v_mad_u64_u32 v[8:9], s[6:7], s10, v0, v[4:5]
	v_permlane16_swap_b32_e32 v6, v23
	v_permlane16_swap_b32_e32 v15, v17
	s_nop 1
	v_permlane32_swap_b32_e32 v6, v15
	v_permlane32_swap_b32_e32 v23, v17
	s_mov_b32 s6, 0x5010400
	s_mov_b32 s7, 0x7030602
	v_perm_b32 v3, v23, v6, s6
	v_perm_b32 v7, v23, v6, s7
	v_perm_b32 v5, v17, v15, s6
	v_perm_b32 v15, v17, v15, s7
	s_mov_b32 s8, 0x5040100
	s_mov_b32 s9, 0x7060302
	v_permlane16_swap_b32_e32 v10, v19
	v_permlane16_swap_b32_e32 v12, v13
	v_perm_b32 v4, v5, v3, s8
	v_perm_b32 v5, v5, v3, s9
	v_perm_b32 v6, v15, v7, s8
	v_perm_b32 v7, v15, v7, s9
	v_permlane32_swap_b32_e32 v10, v12
	v_permlane32_swap_b32_e32 v19, v13
	global_store_dwordx4 v[8:9], v[4:7], off
	v_perm_b32 v3, v19, v10, s6
	v_permlane16_swap_b32_e32 v2, v18
	v_perm_b32 v7, v19, v10, s7
	v_perm_b32 v5, v13, v12, s6
	v_perm_b32 v10, v13, v12, s7
	v_permlane16_swap_b32_e32 v11, v20
	v_perm_b32 v4, v5, v3, s8
	v_perm_b32 v5, v5, v3, s9
	v_perm_b32 v6, v10, v7, s8
	v_perm_b32 v7, v10, v7, s9
	v_permlane32_swap_b32_e32 v2, v11
	v_permlane32_swap_b32_e32 v18, v20
	global_store_dwordx4 v[8:9], v[4:7], off offset:16
	v_perm_b32 v3, v18, v2, s6
	v_permlane16_swap_b32_e32 v14, v22
	v_perm_b32 v5, v18, v2, s7
	v_perm_b32 v4, v20, v11, s6
	v_perm_b32 v6, v20, v11, s7
	v_permlane16_swap_b32_e32 v16, v21
	v_perm_b32 v2, v4, v3, s8
	v_perm_b32 v3, v4, v3, s9
	v_perm_b32 v4, v6, v5, s8
	v_perm_b32 v5, v6, v5, s9
	v_permlane32_swap_b32_e32 v14, v16
	v_permlane32_swap_b32_e32 v22, v21
	global_store_dwordx4 v[8:9], v[2:5], off offset:32
	v_perm_b32 v6, v21, v16, s7
	s_nop 0
	v_perm_b32 v3, v22, v14, s6
	v_perm_b32 v5, v22, v14, s7
	v_perm_b32 v4, v21, v16, s6
	v_perm_b32 v2, v4, v3, s8
	v_perm_b32 v3, v4, v3, s9
	v_perm_b32 v4, v6, v5, s8
	v_perm_b32 v5, v6, v5, s9
	global_store_dwordx4 v[8:9], v[2:5], off offset:48
	s_cbranch_scc1 .LBB0_2106
